# column-sum partials of the prologue loaded together instead of one dependent load at a time
# baseline (speedup 1.0000x reference)
; __global__ void __launch_bounds__(NWAVES * 64) mega(Args a) {
;     ...
;             for (int i = blockIdx.x * 512 + tid; i < DEPTH * 2 * CSN; i += G * 512) { const int lc = i / CSN, c = i % CSN; const float* pp = CSP + (size_t)lc * 16 * CSN + c; float s = 0.f;
; #pragma unroll
;                 for (int kb = 0; kb < 16; ++kb) s += pp[kb * CSN];
;                 CS[i] = s; }
.LBB0_29:
	s_mov_b32 s6, 0xdd67c8a7
	v_mul_hi_i32 v1, v0, s6
	v_add_u32_e32 v1, v1, v0
	v_lshrrev_b32_e32 v2, 31, v1
	v_ashrrev_i32_e32 v1, 13, v1
	v_add_u32_e32 v1, v1, v2
	v_mul_i32_i24_e32 v2, 0x2500, v1
	v_sub_u32_e32 v2, v0, v2
	v_mul_hi_i32_i24_e32 v5, 0x94000, v1
	v_mul_i32_i24_e32 v4, 0x94000, v1
	v_lshl_add_u64 v[4:5], s[84:85], 0, v[4:5]
	v_ashrrev_i32_e32 v3, 31, v2
	v_lshl_add_u64 v[2:3], v[2:3], 2, v[4:5]
	v_mov_b32_e32 v180, v2
	v_mov_b32_e32 v181, v3
	s_mov_b64 vcc, 0x9400
	global_load_dword v182, v[180:181], off
	v_lshl_add_u64 v[180:181], v[180:181], 0, vcc
	global_load_dword v183, v[180:181], off
	v_lshl_add_u64 v[180:181], v[180:181], 0, vcc
	global_load_dword v184, v[180:181], off
	v_lshl_add_u64 v[180:181], v[180:181], 0, vcc
	global_load_dword v185, v[180:181], off
	v_lshl_add_u64 v[180:181], v[180:181], 0, vcc
	global_load_dword v186, v[180:181], off
	v_lshl_add_u64 v[180:181], v[180:181], 0, vcc
	global_load_dword v187, v[180:181], off
	v_lshl_add_u64 v[180:181], v[180:181], 0, vcc
	global_load_dword v188, v[180:181], off
	v_lshl_add_u64 v[180:181], v[180:181], 0, vcc
	global_load_dword v189, v[180:181], off
	v_lshl_add_u64 v[180:181], v[180:181], 0, vcc
	global_load_dword v190, v[180:181], off
	v_lshl_add_u64 v[180:181], v[180:181], 0, vcc
	global_load_dword v191, v[180:181], off
	v_lshl_add_u64 v[180:181], v[180:181], 0, vcc
	global_load_dword v192, v[180:181], off
	v_lshl_add_u64 v[180:181], v[180:181], 0, vcc
	global_load_dword v193, v[180:181], off
	v_lshl_add_u64 v[180:181], v[180:181], 0, vcc
	global_load_dword v194, v[180:181], off
	v_lshl_add_u64 v[180:181], v[180:181], 0, vcc
	global_load_dword v195, v[180:181], off
	v_lshl_add_u64 v[180:181], v[180:181], 0, vcc
	global_load_dword v196, v[180:181], off
	v_lshl_add_u64 v[180:181], v[180:181], 0, vcc
	global_load_dword v197, v[180:181], off
	s_mov_b32 s6, 0x127ff
	s_waitcnt vmcnt(0)
	v_add_f32_e32 v1, 0, v182
	v_add_f32_e32 v1, v1, v183
	v_add_f32_e32 v1, v1, v184
	v_add_f32_e32 v1, v1, v185
	v_add_f32_e32 v1, v1, v186
	v_add_f32_e32 v1, v1, v187
	v_add_f32_e32 v1, v1, v188
	v_add_f32_e32 v1, v1, v189
	v_add_f32_e32 v1, v1, v190
	v_add_f32_e32 v1, v1, v191
	v_add_f32_e32 v1, v1, v192
	v_add_f32_e32 v1, v1, v193
	v_add_f32_e32 v1, v1, v194
	v_add_f32_e32 v1, v1, v195
	v_add_f32_e32 v1, v1, v196
	v_add_f32_e32 v4, v1, v197
	v_ashrrev_i32_e32 v1, 31, v0
	v_lshl_add_u64 v[2:3], v[0:1], 2, s[12:13]
	v_add_u32_e32 v0, s56, v0
	v_cmp_lt_i32_e32 vcc, s6, v0
	s_or_b64 s[10:11], vcc, s[10:11]
	global_store_dword v[2:3], v4, off
	s_andn2_b64 exec, exec, s[10:11]
	s_cbranch_execnz .LBB0_29
